# v19 + rg_item<1> conv stage: the 35 serial ds_read_u16 x_r reads hoisted as in rg_item<3>
# baseline (speedup 1.0000x reference)
.LBB0_707:
	s_or_b64 exec, exec, s[4:5]
	s_lshr_b32 s4, s13, 6
	s_mulk_i32 s4, 0x1200
	s_load_dwordx4 s[40:43], s[60:61], 0x50
	s_add_i32 s5, s4, 0
	s_add_i32 s5, s5, 0x18c00
	s_waitcnt lgkmcnt(0)
	s_add_u32 s38, s38, s0
	s_addc_u32 s39, s39, s1
	s_and_b32 s4, s13, 0xffffffc0
	s_waitcnt vmcnt(0)
	v_mov_b32_e32 v0, s13
	s_movk_i32 s11, 0xffc0
	v_bfi_b32 v0, s11, v0, v22
	s_add_u32 s40, s40, s0
	s_addc_u32 s41, s41, s1
	v_ashrrev_i32_e32 v1, 31, v0
	v_add_u32_e32 v8, s8, v0
	v_mov_b32_e32 v2, s42
	v_mov_b32_e32 v3, s43
	v_lshl_add_u64 v[4:5], v[0:1], 2, s[40:41]
	v_ashrrev_i32_e32 v9, 31, v8
	v_add_co_u32_e32 v6, vcc, s3, v4
	v_lshl_add_u64 v[2:3], v[8:9], 2, v[2:3]
	s_nop 0
	v_addc_co_u32_e32 v7, vcc, 0, v5, vcc
	global_load_dword v120, v[2:3], off
	global_load_dword v121, v[4:5], off
	global_load_dword v122, v[4:5], off offset:2048
	global_load_dword v123, v[6:7], off
	global_load_dword v124, v[6:7], off offset:2048
	v_and_b32_e32 v172, 48, v22
	v_lshl_add_u64 v[2:3], s[58:59], 0, v[172:173]
	v_lshl_add_u32 v20, v0, 1, 0
	s_mov_b64 s[40:41], 0x3f2000
	v_lshl_add_u64 v[112:113], v[2:3], 0, s[40:41]
	s_barrier
	ds_read_u16 v182, v20
	ds_read_u16 v183, v20 offset:1024
	ds_read_u16 v184, v20 offset:2048
	ds_read_u16 v185, v20 offset:3072
	ds_read_u16 v186, v20 offset:4096
	ds_read_u16 v187, v20 offset:5120
	ds_read_u16 v188, v20 offset:6144
	ds_read_u16 v189, v20 offset:7168
	ds_read_u16 v190, v20 offset:8192
	ds_read_u16 v191, v20 offset:9216
	ds_read_u16 v192, v20 offset:10240
	ds_read_u16 v193, v20 offset:11264
	ds_read_u16 v194, v20 offset:12288
	ds_read_u16 v195, v20 offset:13312
	ds_read_u16 v196, v20 offset:14336
	ds_read_u16 v197, v20 offset:15360
	ds_read_u16 v198, v20 offset:16384
	ds_read_u16 v199, v20 offset:17408
	ds_read_u16 v200, v20 offset:18432
	ds_read_u16 v201, v20 offset:19456
	ds_read_u16 v202, v20 offset:20480
	ds_read_u16 v203, v20 offset:21504
	ds_read_u16 v214, v20 offset:22528
	ds_read_u16 v215, v20 offset:23552
	ds_read_u16 v216, v20 offset:24576
	ds_read_u16 v217, v20 offset:25600
	ds_read_u16 v218, v20 offset:26624
	ds_read_u16 v219, v20 offset:27648
	ds_read_u16 v220, v20 offset:28672
	ds_read_u16 v221, v20 offset:29696
	ds_read_u16 v222, v20 offset:30720
	ds_read_u16 v223, v20 offset:31744
	ds_read_u16 v224, v20 offset:32768
	ds_read_u16 v225, v20 offset:33792
	ds_read_u16 v226, v20 offset:34816
	s_waitcnt lgkmcnt(0)
	v_and_b32_e32 v17, 63, v22
	v_lshlrev_b32_e32 v0, 16, v182
	v_lshlrev_b32_e32 v1, 16, v183
	v_lshlrev_b32_e32 v4, 16, v184
	v_lshlrev_b32_e32 v3, 16, v185
	v_lshl_add_u32 v21, v17, 1, s5
	s_add_u32 s11, s58, s54
	s_addc_u32 s26, s59, s55
	v_and_b32_e32 v16, 15, v22
	s_add_u32 s48, s11, 0x4000
	v_or_b32_e32 v114, s4, v16
	s_addc_u32 s49, s26, 0
	s_add_i32 s11, s4, 0x200
	s_add_i32 s26, s4, 0x400
	s_add_i32 s29, s4, 0x600
	v_ashrrev_i32_e32 v115, 31, v114
	v_cmp_gt_u32_e64 s[44:45], 16, v17
	v_cmp_lt_u32_e64 s[46:47], 31, v17
	s_waitcnt vmcnt(3)
	v_fma_f32 v0, v121, v0, v120
	s_waitcnt vmcnt(2)
	v_fmac_f32_e32 v0, v122, v1
	s_waitcnt vmcnt(1)
	v_fmac_f32_e32 v0, v123, v4
	s_waitcnt vmcnt(0)
	v_fmac_f32_e32 v0, v124, v3
	v_bfe_u32 v2, v0, 16, 1
	v_add3_u32 v0, v0, v2, s33
	ds_write_b16_d16_hi v21, v0
	v_fma_f32 v1, v121, v1, v120
	v_fmac_f32_e32 v1, v122, v4
	v_fmac_f32_e32 v1, v123, v3
	v_add_u32_e32 v2, 0x400, v114
	v_lshlrev_b32_e32 v6, 16, v186
	v_fmac_f32_e32 v1, v124, v6
	v_bfe_u32 v0, v1, 16, 1
	v_add3_u32 v0, v1, v0, s33
	ds_write_b16_d16_hi v21, v0 offset:144
	v_fma_f32 v1, v121, v4, v120
	v_fmac_f32_e32 v1, v122, v3
	v_fmac_f32_e32 v1, v123, v6
	v_fma_f32 v3, v121, v3, v120
	v_lshlrev_b32_e32 v7, 16, v187
	v_fmac_f32_e32 v1, v124, v7
	v_bfe_u32 v0, v1, 16, 1
	v_add3_u32 v0, v1, v0, s33
	ds_write_b16_d16_hi v21, v0 offset:288
	v_fmac_f32_e32 v3, v122, v6
	v_fmac_f32_e32 v3, v123, v7
	v_fma_f32 v6, v121, v6, v120
	v_fmac_f32_e32 v6, v122, v7
	v_lshlrev_b32_e32 v8, 16, v188
	v_fmac_f32_e32 v3, v124, v8
	v_bfe_u32 v4, v3, 16, 1
	v_add3_u32 v3, v3, v4, s33
	ds_write_b16_d16_hi v21, v3 offset:432
	v_fmac_f32_e32 v6, v123, v8
	v_fma_f32 v7, v121, v7, v120
	v_fmac_f32_e32 v7, v122, v8
	v_lshlrev_b64 v[0:1], 7, v[114:115]
	v_lshlrev_b32_e32 v9, 16, v189
	v_fmac_f32_e32 v6, v124, v9
	v_bfe_u32 v3, v6, 16, 1
	v_add3_u32 v3, v6, v3, s33
	ds_write_b16_d16_hi v21, v3 offset:576
	v_fmac_f32_e32 v7, v123, v9
	v_lshlrev_b64 v[4:5], 2, v[114:115]
	v_ashrrev_i32_e32 v3, 31, v2
	v_lshl_add_u64 v[0:1], v[112:113], 0, v[0:1]
	v_lshlrev_b32_e32 v10, 16, v190
	v_fmac_f32_e32 v7, v124, v10
	v_bfe_u32 v6, v7, 16, 1
	v_add3_u32 v6, v7, v6, s33
	ds_write_b16_d16_hi v21, v6 offset:720
	v_fma_f32 v7, v121, v8, v120
	v_fmac_f32_e32 v7, v122, v9
	v_fmac_f32_e32 v7, v123, v10
	v_lshl_add_u64 v[2:3], v[2:3], 2, s[38:39]
	v_lshlrev_b32_e32 v8, 16, v191
	v_fmac_f32_e32 v7, v124, v8
	v_bfe_u32 v6, v7, 16, 1
	v_add3_u32 v6, v7, v6, s33
	ds_write_b16_d16_hi v21, v6 offset:864
	v_fma_f32 v7, v121, v9, v120
	v_fmac_f32_e32 v7, v122, v10
	v_fmac_f32_e32 v7, v123, v8
	v_fma_f32 v10, v121, v10, v120
	v_lshlrev_b32_e32 v9, 16, v192
	v_fmac_f32_e32 v7, v124, v9
	v_bfe_u32 v6, v7, 16, 1
	v_add3_u32 v6, v7, v6, s33
	ds_write_b16_d16_hi v21, v6 offset:1008
	v_fmac_f32_e32 v10, v122, v8
	v_fmac_f32_e32 v10, v123, v9
	v_fma_f32 v8, v121, v8, v120
	v_fmac_f32_e32 v8, v122, v9
	v_lshlrev_b32_e32 v11, 16, v193
	v_fmac_f32_e32 v10, v124, v11
	v_bfe_u32 v12, v10, 16, 1
	v_add3_u32 v10, v10, v12, s33
	ds_write_b16_d16_hi v21, v10 offset:1152
	v_fmac_f32_e32 v8, v123, v11
	v_fma_f32 v9, v121, v9, v120
	v_fmac_f32_e32 v9, v122, v11
	v_fma_f32 v11, v121, v11, v120
	v_lshlrev_b32_e32 v10, 16, v194
	v_fmac_f32_e32 v8, v124, v10
	v_bfe_u32 v12, v8, 16, 1
	v_add3_u32 v8, v8, v12, s33
	ds_write_b16_d16_hi v21, v8 offset:1296
	v_fmac_f32_e32 v9, v123, v10
	v_fmac_f32_e32 v11, v122, v10
	v_fma_f32 v10, v121, v10, v120
	v_lshl_add_u64 v[6:7], s[38:39], 0, v[4:5]
	v_lshlrev_b32_e32 v8, 16, v195
	v_fmac_f32_e32 v9, v124, v8
	v_bfe_u32 v12, v9, 16, 1
	v_add3_u32 v9, v9, v12, s33
	ds_write_b16_d16_hi v21, v9 offset:1440
	v_fmac_f32_e32 v11, v123, v8
	v_fmac_f32_e32 v10, v122, v8
	v_fma_f32 v8, v121, v8, v120
	v_lshl_add_u64 v[4:5], s[48:49], 0, v[4:5]
	v_lshlrev_b32_e32 v9, 16, v196
	v_fmac_f32_e32 v11, v124, v9
	v_bfe_u32 v12, v11, 16, 1
	v_add3_u32 v11, v11, v12, s33
	ds_write_b16_d16_hi v21, v11 offset:1584
	v_fmac_f32_e32 v10, v123, v9
	v_fmac_f32_e32 v8, v122, v9
	v_fma_f32 v9, v121, v9, v120
	v_lshlrev_b32_e32 v11, 16, v197
	v_fmac_f32_e32 v10, v124, v11
	v_bfe_u32 v12, v10, 16, 1
	v_add3_u32 v10, v10, v12, s33
	ds_write_b16_d16_hi v21, v10 offset:1728
	v_fmac_f32_e32 v8, v123, v11
	v_fmac_f32_e32 v9, v122, v11
	v_fma_f32 v11, v121, v11, v120
	v_lshlrev_b32_e32 v10, 16, v198
	v_fmac_f32_e32 v8, v124, v10
	v_bfe_u32 v12, v8, 16, 1
	v_add3_u32 v8, v8, v12, s33
	ds_write_b16_d16_hi v21, v8 offset:1872
	v_fmac_f32_e32 v9, v123, v10
	v_fmac_f32_e32 v11, v122, v10
	v_fma_f32 v10, v121, v10, v120
	v_lshlrev_b32_e32 v12, 16, v199
	v_fmac_f32_e32 v9, v124, v12
	v_bfe_u32 v8, v9, 16, 1
	v_add3_u32 v8, v9, v8, s33
	ds_write_b16_d16_hi v21, v8 offset:2016
	v_fmac_f32_e32 v11, v123, v12
	v_fmac_f32_e32 v10, v122, v12
	v_fma_f32 v12, v121, v12, v120
	v_or_b32_e32 v8, s11, v16
	v_lshlrev_b32_e32 v9, 16, v200
	v_fmac_f32_e32 v11, v124, v9
	v_bfe_u32 v13, v11, 16, 1
	v_add3_u32 v11, v11, v13, s33
	ds_write_b16_d16_hi v21, v11 offset:2160
	v_fmac_f32_e32 v10, v123, v9
	v_fmac_f32_e32 v12, v122, v9
	v_fma_f32 v9, v121, v9, v120
	s_mov_b32 s11, 0
	v_lshlrev_b32_e32 v11, 16, v201
	v_fmac_f32_e32 v10, v124, v11
	v_bfe_u32 v13, v10, 16, 1
	v_add3_u32 v10, v10, v13, s33
	ds_write_b16_d16_hi v21, v10 offset:2304
	v_fmac_f32_e32 v12, v123, v11
	v_fmac_f32_e32 v9, v122, v11
	v_fma_f32 v11, v121, v11, v120
	v_or_b32_e32 v10, s26, v16
	v_lshlrev_b32_e32 v13, 16, v202
	v_fmac_f32_e32 v12, v124, v13
	v_bfe_u32 v14, v12, 16, 1
	v_add3_u32 v12, v12, v14, s33
	ds_write_b16_d16_hi v21, v12 offset:2448
	v_fmac_f32_e32 v9, v123, v13
	v_fmac_f32_e32 v11, v122, v13
	v_fma_f32 v13, v121, v13, v120
	v_or_b32_e32 v12, s29, v16
	v_lshlrev_b32_e32 v14, 16, v203
	v_fmac_f32_e32 v9, v124, v14
	v_bfe_u32 v15, v9, 16, 1
	v_add3_u32 v9, v9, v15, s33
	ds_write_b16_d16_hi v21, v9 offset:2592
	v_fmac_f32_e32 v11, v123, v14
	v_fmac_f32_e32 v13, v122, v14
	v_fma_f32 v14, v121, v14, v120
	v_ashrrev_i32_e32 v9, 31, v8
	v_lshlrev_b32_e32 v15, 16, v214
	v_fmac_f32_e32 v11, v124, v15
	v_bfe_u32 v18, v11, 16, 1
	v_add3_u32 v11, v11, v18, s33
	ds_write_b16_d16_hi v21, v11 offset:2736
	v_fmac_f32_e32 v13, v123, v15
	v_fmac_f32_e32 v14, v122, v15
	v_fma_f32 v15, v121, v15, v120
	v_ashrrev_i32_e32 v11, 31, v10
	v_lshlrev_b32_e32 v23, 16, v215
	v_fmac_f32_e32 v13, v124, v23
	v_bfe_u32 v18, v13, 16, 1
	v_add3_u32 v13, v13, v18, s33
	ds_write_b16_d16_hi v21, v13 offset:2880
	v_fmac_f32_e32 v14, v123, v23
	v_fmac_f32_e32 v15, v122, v23
	v_fma_f32 v23, v121, v23, v120
	v_ashrrev_i32_e32 v13, 31, v12
	v_lshlrev_b32_e32 v24, 16, v216
	v_fmac_f32_e32 v14, v124, v24
	v_bfe_u32 v18, v14, 16, 1
	v_add3_u32 v14, v14, v18, s33
	ds_write_b16_d16_hi v21, v14 offset:3024
	v_fmac_f32_e32 v15, v123, v24
	v_fmac_f32_e32 v23, v122, v24
	v_fma_f32 v24, v121, v24, v120
	v_add_u32_e32 v14, 0x400, v8
	v_lshlrev_b32_e32 v25, 16, v217
	v_fmac_f32_e32 v15, v124, v25
	v_bfe_u32 v18, v15, 16, 1
	v_add3_u32 v15, v15, v18, s33
	ds_write_b16_d16_hi v21, v15 offset:3168
	v_fmac_f32_e32 v23, v123, v25
	v_fmac_f32_e32 v24, v122, v25
	v_fma_f32 v25, v121, v25, v120
	v_lshlrev_b64 v[18:19], 7, v[8:9]
	v_lshlrev_b32_e32 v15, 16, v218
	v_fmac_f32_e32 v23, v124, v15
	v_bfe_u32 v26, v23, 16, 1
	v_add3_u32 v23, v23, v26, s33
	ds_write_b16_d16_hi v21, v23 offset:3312
	v_fmac_f32_e32 v24, v123, v15
	v_fmac_f32_e32 v25, v122, v15
	v_fma_f32 v15, v121, v15, v120
	v_lshlrev_b64 v[10:11], 7, v[10:11]
	v_lshlrev_b32_e32 v23, 16, v219
	v_fmac_f32_e32 v24, v124, v23
	v_bfe_u32 v26, v24, 16, 1
	v_add3_u32 v24, v24, v26, s33
	ds_write_b16_d16_hi v21, v24 offset:3456
	v_fmac_f32_e32 v25, v123, v23
	v_fmac_f32_e32 v15, v122, v23
	v_fma_f32 v23, v121, v23, v120
	v_lshlrev_b64 v[12:13], 7, v[12:13]
	v_lshlrev_b32_e32 v24, 16, v220
	v_fmac_f32_e32 v25, v124, v24
	v_bfe_u32 v26, v25, 16, 1
	v_add3_u32 v25, v25, v26, s33
	ds_write_b16_d16_hi v21, v25 offset:3600
	v_fmac_f32_e32 v15, v123, v24
	v_fmac_f32_e32 v23, v122, v24
	v_fma_f32 v24, v121, v24, v120
	v_lshl_add_u64 v[8:9], v[8:9], 2, s[38:39]
	v_lshlrev_b32_e32 v25, 16, v221
	v_fmac_f32_e32 v15, v124, v25
	v_bfe_u32 v26, v15, 16, 1
	v_add3_u32 v15, v15, v26, s33
	ds_write_b16_d16_hi v21, v15 offset:3744
	v_fmac_f32_e32 v23, v123, v25
	v_fmac_f32_e32 v24, v122, v25
	v_fma_f32 v25, v121, v25, v120
	v_ashrrev_i32_e32 v15, 31, v14
	v_lshlrev_b32_e32 v26, 16, v222
	v_fmac_f32_e32 v23, v124, v26
	v_bfe_u32 v27, v23, 16, 1
	v_add3_u32 v23, v23, v27, s33
	ds_write_b16_d16_hi v21, v23 offset:3888
	v_fmac_f32_e32 v24, v123, v26
	v_fmac_f32_e32 v25, v122, v26
	v_fma_f32 v26, v121, v26, v120
	v_lshl_add_u64 v[18:19], v[112:113], 0, v[18:19]
	v_lshlrev_b32_e32 v23, 16, v223
	v_fmac_f32_e32 v24, v124, v23
	v_bfe_u32 v27, v24, 16, 1
	v_add3_u32 v24, v24, v27, s33
	ds_write_b16_d16_hi v21, v24 offset:4032
	v_fmac_f32_e32 v25, v123, v23
	v_fmac_f32_e32 v26, v122, v23
	v_fma_f32 v23, v121, v23, v120
	v_lshl_add_u64 v[10:11], v[112:113], 0, v[10:11]
	v_lshlrev_b32_e32 v24, 16, v224
	v_fmac_f32_e32 v25, v124, v24
	v_bfe_u32 v27, v25, 16, 1
	v_add3_u32 v25, v25, v27, s33
	ds_write_b16_d16_hi v21, v25 offset:4176
	v_fmac_f32_e32 v26, v123, v24
	v_fmac_f32_e32 v23, v122, v24
	v_lshl_add_u64 v[12:13], v[112:113], 0, v[12:13]
	v_lshl_add_u64 v[14:15], v[14:15], 2, s[38:39]
	v_lshlrev_b32_e32 v25, 16, v225
	v_fmac_f32_e32 v26, v124, v25
	v_bfe_u32 v27, v26, 16, 1
	v_add3_u32 v26, v26, v27, s33
	ds_write_b16_d16_hi v21, v26 offset:4320
	v_fmac_f32_e32 v23, v123, v25
	s_ashr_i32 s29, s28, 31
	s_lshl_b64 s[28:29], s[28:29], 13
	s_add_u32 s28, s58, s28
	v_lshlrev_b32_e32 v20, 16, v226
	v_fmac_f32_e32 v23, v124, v20
	v_bfe_u32 v20, v23, 16, 1
	v_add3_u32 v20, v23, v20, s33
	ds_write_b16_d16_hi v21, v20 offset:4464
	s_waitcnt lgkmcnt(0)
	global_load_dwordx4 v[64:67], v[0:1], off
	global_load_dwordx4 v[72:75], v[0:1], off offset:64
	global_load_dwordx4 v[68:71], v[18:19], off
	global_load_dwordx4 v[76:79], v[18:19], off offset:64
	global_load_dword v92, v[6:7], off
	global_load_dword v91, v[8:9], off
	global_load_dwordx4 v[56:59], v[10:11], off offset:64
	global_load_dwordx4 v[52:55], v[12:13], off
	global_load_dwordx4 v[60:63], v[12:13], off offset:64
	global_load_dword v84, v[2:3], off
	global_load_dword v83, v[14:15], off
	global_load_dword v89, v[4:5], off
	global_load_dwordx4 v[48:51], v[10:11], off
	global_load_dword v82, v[4:5], off offset:2048
	s_addc_u32 s29, s59, s29
	v_mul_u32_u24_e32 v0, 0x90, v16
	s_add_u32 s58, s28, 0x432000
	v_bfe_u32 v18, v22, 4, 2
	v_add3_u32 v12, s5, v172, v0
	s_addc_u32 s59, s29, 0
	ds_read_b128 v[0:3], v12
	ds_read_b128 v[4:7], v12 offset:64
	ds_read_b128 v[8:11], v12 offset:2304
	ds_read_b128 v[12:15], v12 offset:2368
	v_and_b32_e32 v19, 64, v212
	v_xor_b32_e32 v20, 2, v18
	s_add_u32 s60, s28, 0x433000
	v_add_u32_e32 v21, 16, v22
	v_cmp_lt_u32_e64 s[42:43], 1, v20
	v_or_b32_e32 v20, v19, v16
	s_addc_u32 s61, s29, 0
	s_lshl_b32 s5, s13, 1
	v_and_or_b32 v21, v21, 63, v19
	v_lshlrev_b32_e32 v127, 2, v20
	v_add_u32_e32 v20, 48, v22
	s_ashr_i32 s4, s4, 31
	s_and_b32 s5, s5, 0xffffff80
	v_lshlrev_b32_e32 v125, 2, v21
	v_or_b32_e32 v21, v19, v17
	v_and_or_b32 v19, v20, 63, v19
	v_lshl_add_u32 v17, v18, 12, s5
	v_mov_b32_e32 v115, s4
	v_cmp_eq_u32_e64 s[40:41], 3, v18
	v_lshlrev_b32_e32 v128, 2, v19
	v_lshl_or_b32 v17, v16, 1, v17
	v_lshl_add_u64 v[18:19], v[114:115], 3, s[28:29]
	s_mov_b64 s[4:5], 0x432084
	v_lshlrev_b32_e32 v21, 2, v21
	v_add_u32_e32 v130, 0, v17
	v_lshl_add_u64 v[116:117], v[18:19], 0, s[4:5]
	v_lshlrev_b32_e32 v17, 2, v212
	v_lshlrev_b32_e32 v16, 2, v16
	s_movk_i32 s4, 0x100
	v_xor_b32_e32 v126, 0x80, v21
	v_or_b32_e32 v129, 0xc0, v21
	v_and_or_b32 v115, v17, s4, v16
	s_branch .LBB0_709
